# attention item epilogue hand-written: 4x4 lane/register transpose (permlane16/32 swaps) -> 16-byte partial-output stores
# speedup vs baseline: 1.0147x; 1.0147x over previous
.LBB0_331:
	s_waitcnt vmcnt(6)
	v_mov_b64_e32 v[78:79], v[98:99]
	v_mov_b64_e32 v[82:83], v[94:95]
	v_mov_b64_e32 v[70:71], v[90:91]
	v_mov_b64_e32 v[74:75], v[86:87]
	s_andn2_b64 vcc, exec, s[26:27]
	v_mov_b64_e32 v[80:81], v[100:101]
	v_mov_b64_e32 v[84:85], v[96:97]
	v_mov_b64_e32 v[72:73], v[92:93]
	v_mov_b64_e32 v[76:77], v[88:89]
	s_mov_b32 s16, s49
	s_mov_b32 s17, s29
	s_mov_b32 s18, s48
	s_mov_b64 s[20:21], s[30:31]
	s_mov_b32 s14, s28
	s_barrier
	s_cbranch_vccz .LBB0_375

.Lattn_end4:
	s_ashr_i32 s19, s18, 31
	s_lshl_b64 s[6:7], s[18:19], 14
	s_add_u32 s18, s6, s20
	s_addc_u32 s19, s7, s21
	s_lshl_b64 s[6:7], s[18:19], 5
	s_add_u32 s6, s24, s6
	s_addc_u32 s7, s25, s7
	s_lshl_b32 s9, s16, 2
	s_add_u32 s6, s6, s9
	s_addc_u32 s7, s7, 0
	s_lshl_b64 s[10:11], s[18:19], 10
	s_add_u32 s10, s22, s10
	s_addc_u32 s11, s23, s11
	s_lshl_b32 s9, s16, 7
	s_add_u32 s10, s10, s9
	s_addc_u32 s11, s11, 0
	v_mul_u32_u24_e32 v1, s14, v17
	v_lshlrev_b32_e32 v2, 10, v1
	v_lshl_add_u32 v2, v148, 5, v2
	v_lshlrev_b32_e32 v3, 5, v1
	v_cvt_pk_bf16_f32 v150, v134, v135
	v_cvt_pk_bf16_f32 v151, v136, v137
	v_cvt_pk_bf16_f32 v152, v130, v131
	v_cvt_pk_bf16_f32 v153, v132, v133
	v_cvt_pk_bf16_f32 v154, v126, v127
	v_cvt_pk_bf16_f32 v155, v128, v129
	v_cvt_pk_bf16_f32 v156, v122, v123
	v_cvt_pk_bf16_f32 v157, v124, v125
	v_cvt_pk_bf16_f32 v158, v114, v115
	v_cvt_pk_bf16_f32 v159, v116, v117
	v_cvt_pk_bf16_f32 v160, v106, v107
	v_cvt_pk_bf16_f32 v161, v108, v109
	v_cvt_pk_bf16_f32 v162, v110, v111
	v_cvt_pk_bf16_f32 v163, v112, v113
	v_cvt_pk_bf16_f32 v164, v102, v103
	v_cvt_pk_bf16_f32 v165, v104, v105
	s_nop 1
	v_permlane32_swap_b32_e32 v150, v154
	v_permlane32_swap_b32_e32 v152, v156
	v_permlane32_swap_b32_e32 v151, v155
	v_permlane32_swap_b32_e32 v153, v157
	v_permlane32_swap_b32_e32 v158, v162
	v_permlane32_swap_b32_e32 v160, v164
	v_permlane32_swap_b32_e32 v159, v163
	v_permlane32_swap_b32_e32 v161, v165
	s_nop 1
	v_permlane16_swap_b32_e32 v150, v152
	v_permlane16_swap_b32_e32 v154, v156
	v_permlane16_swap_b32_e32 v151, v153
	v_permlane16_swap_b32_e32 v155, v157
	v_permlane16_swap_b32_e32 v158, v160
	v_permlane16_swap_b32_e32 v162, v164
	v_permlane16_swap_b32_e32 v159, v161
	v_permlane16_swap_b32_e32 v163, v165
	global_store_dwordx4 v2, v[150:153], s[10:11]
	global_store_dwordx4 v2, v[154:157], s[10:11] offset:16
	s_lshl_b32 s9, s14, 14
	s_add_u32 s10, s10, s9
	s_addc_u32 s11, s11, 0
	global_store_dwordx4 v2, v[158:161], s[10:11]
	global_store_dwordx4 v2, v[162:165], s[10:11] offset:16
	v_cmp_eq_u32_e32 vcc, 0, v148
	s_and_saveexec_b64 s[34:35], vcc
	global_store_dword v3, v138, s[6:7]
	s_lshl_b32 s9, s14, 9
	s_add_u32 s6, s6, s9
	s_addc_u32 s7, s7, 0
	global_store_dword v3, v118, s[6:7]
	s_or_b64 exec, exec, s[34:35]
	s_branch .LBB0_331
